# baseline (speedup 1.0000x reference)
; template <int MODE> ...
;     ...
;   if (t_q < LP) {
;     bf16_t* obase = Og + row_q * DM + ((MODE == 0) ? 1024 : 0) + h * 128 + 4 * g;
; #pragma unroll
;     for (int mb = 0; mb < 4; ++mb)
; #pragma unroll
;       for (int ii = 0; ii < 4; ++ii)
;         store4bf(obase + mb * 32 + 8 * ii, O[mb][4 * ii] * inv, O[mb][4 * ii + 1] * inv, O[mb][4 * ii + 2] * inv,
;                  O[mb][4 * ii + 3] * inv);
;   }
.LBB0_344:
	s_movk_i32 s2, 0x2010
	v_cmp_gt_i32_e32 vcc, s2, v146
	s_mov_b64 s[6:7], 0
	s_mov_b64 s[2:3], 0
	s_and_saveexec_b64 s[8:9], vcc
	s_xor_b64 s[8:9], exec, s[8:9]
	s_cbranch_execz .LBB0_346
	v_lshlrev_b64 v[2:3], 12, v[144:145]
	v_lshl_add_u64 v[2:3], s[62:63], 0, v[2:3]
	s_lshl_b32 s74, s60, 1
	v_lshl_add_u64 v[2:3], v[2:3], 0, s[74:75]
	v_lshlrev_b32_e32 v0, 1, v158
	v_lshl_add_u64 v[2:3], v[2:3], 0, v[0:1]
	v_lshl_add_u64 v[8:9], v[2:3], 0, v[0:1]
	v_cvt_pk_bf16_f32 v4, v64, v65
	v_cvt_pk_bf16_f32 v5, v66, v67
	v_cvt_pk_bf16_f32 v6, v68, v69
	v_cvt_pk_bf16_f32 v7, v70, v71
	s_nop 1
	v_permlane32_swap_b32 v4, v6
	v_permlane32_swap_b32 v5, v7
	global_store_dwordx4 v[8:9], v[4:7], off
	s_nop 1
	v_cvt_pk_bf16_f32 v4, v72, v73
	v_cvt_pk_bf16_f32 v5, v74, v75
	v_cvt_pk_bf16_f32 v6, v76, v77
	v_cvt_pk_bf16_f32 v7, v78, v79
	s_nop 1
	v_permlane32_swap_b32 v4, v6
	v_permlane32_swap_b32 v5, v7
	global_store_dwordx4 v[8:9], v[4:7], off offset:32
	s_nop 1
	v_cvt_pk_bf16_f32 v4, v48, v49
	v_cvt_pk_bf16_f32 v5, v50, v51
	v_cvt_pk_bf16_f32 v6, v52, v53
	v_cvt_pk_bf16_f32 v7, v54, v55
	s_nop 1
	v_permlane32_swap_b32 v4, v6
	v_permlane32_swap_b32 v5, v7
	global_store_dwordx4 v[8:9], v[4:7], off offset:64
	s_nop 1
	v_cvt_pk_bf16_f32 v4, v56, v57
	v_cvt_pk_bf16_f32 v5, v58, v59
	v_cvt_pk_bf16_f32 v6, v60, v61
	v_cvt_pk_bf16_f32 v7, v62, v63
	s_nop 1
	v_permlane32_swap_b32 v4, v6
	v_permlane32_swap_b32 v5, v7
	global_store_dwordx4 v[8:9], v[4:7], off offset:96
	s_nop 1
	v_cvt_pk_bf16_f32 v4, v32, v33
	v_cvt_pk_bf16_f32 v5, v34, v35
	v_cvt_pk_bf16_f32 v6, v36, v37
	v_cvt_pk_bf16_f32 v7, v38, v39
	s_nop 1
	v_permlane32_swap_b32 v4, v6
	v_permlane32_swap_b32 v5, v7
	global_store_dwordx4 v[8:9], v[4:7], off offset:128
	s_nop 1
	v_cvt_pk_bf16_f32 v4, v40, v41
	v_cvt_pk_bf16_f32 v5, v42, v43
	v_cvt_pk_bf16_f32 v6, v44, v45
	v_cvt_pk_bf16_f32 v7, v46, v47
	s_nop 1
	v_permlane32_swap_b32 v4, v6
	v_permlane32_swap_b32 v5, v7
	global_store_dwordx4 v[8:9], v[4:7], off offset:160
	s_nop 1
	v_cvt_pk_bf16_f32 v4, v16, v17
	v_cvt_pk_bf16_f32 v5, v18, v19
	v_cvt_pk_bf16_f32 v6, v20, v21
	v_cvt_pk_bf16_f32 v7, v22, v23
	s_nop 1
	v_permlane32_swap_b32 v4, v6
	v_permlane32_swap_b32 v5, v7
	global_store_dwordx4 v[8:9], v[4:7], off offset:192
	s_nop 1
	v_cvt_pk_bf16_f32 v4, v24, v25
	v_cvt_pk_bf16_f32 v5, v26, v27
	v_cvt_pk_bf16_f32 v0, v28, v29
	s_mov_b64 s[2:3], exec
	global_store_dwordx2 v[2:3], v[4:5], off offset:224
	global_store_dword v[2:3], v0, off offset:240

; template <int MODE> ...
;     ...
;   float inv = 1.f;
;   if (MODE == 0) {
;     const float lt = l_run + __shfl_xor(l_run, 32);
;     inv = 1.f / lt;
;   }
;   if (t_q < LP) {
;     bf16_t* obase = Og + row_q * DM + ((MODE == 0) ? 1024 : 0) + h * 128 + 4 * g;
; #pragma unroll
;     for (int mb = 0; mb < 4; ++mb)
; #pragma unroll
;       for (int ii = 0; ii < 4; ++ii)
;         store4bf(obase + mb * 32 + 8 * ii, O[mb][4 * ii] * inv, O[mb][4 * ii + 1] * inv, O[mb][4 * ii + 2] * inv,
;                  O[mb][4 * ii + 3] * inv);
;   }
.LBB0_373:
	v_cmp_lt_i32_e32 vcc, v199, v198
	s_movk_i32 s6, 0x2010
	s_nop 0
	v_cndmask_b32_e32 v0, v185, v199, vcc
	v_lshlrev_b32_e32 v0, 2, v0
	ds_bpermute_b32 v0, v0, v216
	v_cmp_gt_i32_e32 vcc, s6, v30
	s_and_saveexec_b64 s[6:7], vcc
	s_cbranch_execz .LBB0_375
	s_waitcnt lgkmcnt(0)
	v_add_f32_e32 v0, v216, v0
	v_div_scale_f32 v2, s[8:9], v0, v0, 1.0
	v_rcp_f32_e32 v3, v2
	v_div_scale_f32 v4, vcc, 1.0, v0, 1.0
	s_lshl_b32 s74, s12, 1
	v_fma_f32 v5, -v2, v3, 1.0
	v_fmac_f32_e32 v3, v5, v3
	v_mul_f32_e32 v5, v4, v3
	v_fma_f32 v6, -v2, v5, v4
	v_fmac_f32_e32 v5, v6, v3
	v_fma_f32 v2, -v2, v5, v4
	v_div_fmas_f32 v2, v2, v3, v5
	v_div_fixup_f32 v4, v2, v0, 1.0
	v_lshlrev_b64 v[2:3], 12, v[154:155]
	v_lshl_add_u64 v[2:3], s[62:63], 0, v[2:3]
	v_lshl_add_u64 v[2:3], v[2:3], 0, s[74:75]
	v_lshlrev_b32_e32 v0, 1, v165
	v_pk_mul_f32 v[8:9], v[80:81], v[4:5] op_sel_hi:[1,0]
	v_pk_mul_f32 v[10:11], v[82:83], v[4:5] op_sel_hi:[1,0]
	v_lshl_add_u64 v[6:7], v[2:3], 0, v[0:1]
	v_lshl_add_u64 v[14:15], v[6:7], 0, v[0:1]
	v_cvt_pk_bf16_f32 v8, v8, v9
	v_cvt_pk_bf16_f32 v9, v10, v11
	global_store_dwordx2 v[6:7], v[8:9], off offset:2048
	v_pk_mul_f32 v[8:9], v[84:85], v[4:5] op_sel_hi:[1,0]
	v_pk_mul_f32 v[10:11], v[86:87], v[4:5] op_sel_hi:[1,0]
	v_cvt_pk_bf16_f32 v8, v8, v9
	v_cvt_pk_bf16_f32 v9, v10, v11
	global_store_dwordx2 v[6:7], v[8:9], off offset:2064
	v_pk_mul_f32 v[8:9], v[88:89], v[4:5] op_sel_hi:[1,0]
	v_pk_mul_f32 v[10:11], v[90:91], v[4:5] op_sel_hi:[1,0]
	v_cvt_pk_bf16_f32 v8, v8, v9
	v_cvt_pk_bf16_f32 v9, v10, v11
	v_pk_mul_f32 v[10:11], v[92:93], v[4:5] op_sel_hi:[1,0]
	v_pk_mul_f32 v[12:13], v[94:95], v[4:5] op_sel_hi:[1,0]
	v_cvt_pk_bf16_f32 v10, v10, v11
	v_cvt_pk_bf16_f32 v11, v12, v13
	s_nop 1
	v_permlane32_swap_b32 v8, v10
	v_permlane32_swap_b32 v9, v11
	global_store_dwordx4 v[14:15], v[8:11], off offset:2080
	s_nop 1
	v_pk_mul_f32 v[8:9], v[64:65], v[4:5] op_sel_hi:[1,0]
	v_pk_mul_f32 v[10:11], v[66:67], v[4:5] op_sel_hi:[1,0]
	v_cvt_pk_bf16_f32 v8, v8, v9
	v_cvt_pk_bf16_f32 v9, v10, v11
	v_pk_mul_f32 v[10:11], v[68:69], v[4:5] op_sel_hi:[1,0]
	v_pk_mul_f32 v[12:13], v[70:71], v[4:5] op_sel_hi:[1,0]
	v_cvt_pk_bf16_f32 v10, v10, v11
	v_cvt_pk_bf16_f32 v11, v12, v13
	s_nop 1
	v_permlane32_swap_b32 v8, v10
	v_permlane32_swap_b32 v9, v11
	global_store_dwordx4 v[14:15], v[8:11], off offset:2112
	s_nop 1
	v_pk_mul_f32 v[8:9], v[72:73], v[4:5] op_sel_hi:[1,0]
	v_pk_mul_f32 v[10:11], v[74:75], v[4:5] op_sel_hi:[1,0]
	v_cvt_pk_bf16_f32 v8, v8, v9
	v_cvt_pk_bf16_f32 v9, v10, v11
	v_pk_mul_f32 v[10:11], v[76:77], v[4:5] op_sel_hi:[1,0]
	v_pk_mul_f32 v[12:13], v[78:79], v[4:5] op_sel_hi:[1,0]
	v_cvt_pk_bf16_f32 v10, v10, v11
	v_cvt_pk_bf16_f32 v11, v12, v13
	s_nop 1
	v_permlane32_swap_b32 v8, v10
	v_permlane32_swap_b32 v9, v11
	global_store_dwordx4 v[14:15], v[8:11], off offset:2144
	s_nop 1
	v_pk_mul_f32 v[8:9], v[48:49], v[4:5] op_sel_hi:[1,0]
	v_pk_mul_f32 v[10:11], v[50:51], v[4:5] op_sel_hi:[1,0]
	v_cvt_pk_bf16_f32 v8, v8, v9
	v_cvt_pk_bf16_f32 v9, v10, v11
	v_pk_mul_f32 v[10:11], v[52:53], v[4:5] op_sel_hi:[1,0]
	v_pk_mul_f32 v[12:13], v[54:55], v[4:5] op_sel_hi:[1,0]
	v_cvt_pk_bf16_f32 v10, v10, v11
	v_cvt_pk_bf16_f32 v11, v12, v13
	s_nop 1
	v_permlane32_swap_b32 v8, v10
	v_permlane32_swap_b32 v9, v11
	global_store_dwordx4 v[14:15], v[8:11], off offset:2176
	s_nop 1
	v_pk_mul_f32 v[8:9], v[56:57], v[4:5] op_sel_hi:[1,0]
	v_pk_mul_f32 v[10:11], v[58:59], v[4:5] op_sel_hi:[1,0]
	v_cvt_pk_bf16_f32 v8, v8, v9
	v_cvt_pk_bf16_f32 v9, v10, v11
	v_pk_mul_f32 v[10:11], v[60:61], v[4:5] op_sel_hi:[1,0]
	v_pk_mul_f32 v[12:13], v[62:63], v[4:5] op_sel_hi:[1,0]
	v_cvt_pk_bf16_f32 v10, v10, v11
	v_cvt_pk_bf16_f32 v11, v12, v13
	s_nop 1
	v_permlane32_swap_b32 v8, v10
	v_permlane32_swap_b32 v9, v11
	global_store_dwordx4 v[14:15], v[8:11], off offset:2208
	s_nop 1
	v_pk_mul_f32 v[8:9], v[32:33], v[4:5] op_sel_hi:[1,0]
	v_pk_mul_f32 v[10:11], v[34:35], v[4:5] op_sel_hi:[1,0]
	v_cvt_pk_bf16_f32 v8, v8, v9
	v_cvt_pk_bf16_f32 v9, v10, v11
	v_pk_mul_f32 v[10:11], v[36:37], v[4:5] op_sel_hi:[1,0]
	v_pk_mul_f32 v[12:13], v[38:39], v[4:5] op_sel_hi:[1,0]
	v_cvt_pk_bf16_f32 v10, v10, v11
	v_cvt_pk_bf16_f32 v11, v12, v13
	s_nop 1
	v_permlane32_swap_b32 v8, v10
	v_permlane32_swap_b32 v9, v11
	global_store_dwordx4 v[14:15], v[8:11], off offset:2240
	s_nop 1
	v_pk_mul_f32 v[8:9], v[40:41], v[4:5] op_sel_hi:[1,0]
	v_pk_mul_f32 v[10:11], v[42:43], v[4:5] op_sel_hi:[1,0]
	v_cvt_pk_bf16_f32 v8, v8, v9
	v_cvt_pk_bf16_f32 v9, v10, v11
	s_mov_b64 s[8:9], 0x800
	global_store_dwordx2 v[6:7], v[8:9], off offset:2272
	v_pk_mul_f32 v[8:9], v[44:45], v[4:5] op_sel_hi:[1,0]
	v_lshl_add_u64 v[2:3], v[6:7], 0, s[8:9]
	v_pk_mul_f32 v[30:31], v[46:47], v[4:5] op_sel_hi:[1,0]
	v_cvt_pk_bf16_f32 v0, v8, v9
	s_or_b64 s[2:3], s[2:3], exec
	global_store_dword v[6:7], v0, off offset:2288
